# pool wave-unit queue dealt group-major, widest window first (longest units first, one weight block hot at a time); otherwise the vmcnt(0) spread-DMA variant
# speedup vs baseline: 1.0010x; 1.0010x over previous
; __global__ void __launch_bounds__(NTHREADS, 2) mega(Params P) {
;     ...
;             { unsigned* qctr = (unsigned*)(wsl + WS_BAR) + 8 + l; const int npool = (l < DEPTH - 1) ? (TROWS / 32) * 4 : (NBATCH * SEQ / 32) * 4;
;               for (;;) { unsigned wq = 0u; if (lane == 0) wq = __hip_atomic_fetch_add(qctr, 1u, __ATOMIC_RELAXED, __HIP_MEMORY_SCOPE_AGENT);
;                   const int wi = __builtin_amdgcn_readfirstlane((int)wq); if (wi >= npool) break;
;                   int wu = wi; if (l == DEPTH - 1) { const int rc = wi >> 2, rcf = rc + (CTXL / 32) * (1 + rc / (SEQ / 32)); wu = (rcf << 2) | (wi & 3); }
;                   pool_unit(XB, ZB, WPt, pp->pool_scale + l * 512, wu, lane); } }
.LBB0_125:
	s_or_b64 exec, exec, s[42:43]
	s_waitcnt vmcnt(0) lgkmcnt(0)
	v_readfirstlane_b32 s8, v0
	s_cmp_ge_i32 s8, s6
	s_mov_b64 s[42:43], -1
	s_cbranch_scc1 .LBB0_122
	s_lshr_b32 s9, s6, 2
	s_mov_b32 s10, 3
	s_cmp_ge_u32 s8, s9
	s_cbranch_scc0 .Lpool_rm_done
	s_sub_i32 s8, s8, s9
	s_mov_b32 s10, 2
	s_cmp_ge_u32 s8, s9
	s_cbranch_scc0 .Lpool_rm_done
	s_sub_i32 s8, s8, s9
	s_mov_b32 s10, 1
	s_cmp_ge_u32 s8, s9
	s_cbranch_scc0 .Lpool_rm_done
	s_sub_i32 s8, s8, s9
	s_mov_b32 s10, 0
.Lpool_rm_done:
	s_lshl_b32 s8, s8, 2
	s_or_b32 s8, s8, s10
	s_andn2_b64 vcc, exec, s[38:39]
	s_cbranch_vccnz .LBB0_128
	s_ashr_i32 s10, s8, 31
	s_ashr_i32 s9, s8, 2
	s_lshr_b32 s10, s10, 23
	s_add_i32 s9, s9, s10
	s_ashr_i32 s9, s9, 9
	s_lshl_b32 s9, s9, 5
	s_and_b32 s10, s8, -4
	s_add_i32 s10, s10, s9
	s_and_b32 s8, s8, 3
	s_or_b32 s8, s10, s8
	s_add_i32 s8, s8, 32
